# attention sweeps: far/near classification and constant-bias moves before the tile barriers; sweep-1 K read addresses once per unit
# speedup vs baseline: 1.0025x; 1.0013x over previous
; __device__ __forceinline__ int v_st(int k, int c) { const int kk = (k & ~0xC) | ((k & 4) << 1) | ((k & 8) >> 1); return ((kk >> 3) * 4 + (c >> 5)) * 512 + ((kk & 7) * 32 + (c & 31)) * 2; }
; __device__ __forceinline__ int v_rd_base(int lane) { return ((lane & 3) << 3) | (((lane >> 2) & 3) << 6) | (((lane >> 4) & 1) << 5) | (((lane >> 5) & 1) << 8); }
; #define KLOAD(t) do { const bf16* kp_ = Kb + (size_t)((t) * 64 + sr) * 1024 + sc; ks0 = *reinterpret_cast<const bf16x8*>(kp_); ks1 = *reinterpret_cast<const bf16x8*>(kp_ + 32 * 1024); } while (0)
; #define tid ltid()
; template <bool DIFF> ...
;   int tid = threadIdx.x; asm volatile("" : "+v"(tid)); const int wid = tid >> 6, lane = tid & 63, r32 = lane & 31, hi = lane >> 5;
;   char* K_lds = lds; char* V_lds = lds + 16384; float* tab = (float*)(lds + 32768);
;   constexpr float SCALE = DIFF ? 0.125f : 0.08838834764831845f;
;   constexpr float C = SCALE * 1.4426950408889634f;
;   __syncthreads();
;   if (DIFF) { for (int i = tid; i < 257; i += 512) tab[i] = tabg[t5_bucket(i - 128) * 8 + head] * 8.0f; }
;   else      { for (int i = tid; i < 465; i += 512) tab[i] = tabg[head * 465 + i] * 11.313708498984761f; }
;   char* Q_lds = lds + 36864 + wid * 8192;
;   { const bf16* Qw = Qb + (size_t)(wid * 32 + r32) * 1024 + hi * 8;
; #pragma unroll
;     for (int d0 = 0; d0 < 8; ++d0) *reinterpret_cast<bf16x8*>(Q_lds + KSWZ(r32, (d0 * 16 + hi * 8) * 2)) = *reinterpret_cast<const bf16x8*>(Qw + d0 * 16); }
;   const int sr = tid >> 4, sc = (tid & 15) * 8;
;   const int vst0 = v_st(sr, sc), vst1 = v_st(32 + sr, sc), kst0 = KSWZ(sr, sc * 2), kst1 = KSWZ(32 + sr, sc * 2);
;   const int vb0 = (int)(uintptr_t)V_lds + v_rd_base(lane);
;   int rw = 0, rstart = 0;
;   if (!DIFF) { rw = q0 + (wid >> 1); rstart = rw - 4; rstart = rstart < 0 ? 0 : rstart; rstart = rstart > rows - 8 ? rows - 8 : rstart; }
;   const int qbase = q0 + wid * 32;
;   float m1 = -1e30f, l1 = 0.f, m2 = -1e30f, l2 = 0.f;
;   bf16x8 ks0, ks1, vs0, vs1;
;     ...
;   if (DIFF) {
;   KLOAD(t_lo);
.LBB0_274:
	s_or_b64 exec, exec, s[6:7]
	s_lshl_b32 s36, s2, 8
	s_waitcnt lgkmcnt(0)
	s_add_u32 s30, s34, s36
	s_addc_u32 s31, s35, 0
	s_lshl_b64 s[4:5], s[30:31], 11
	v_ashrrev_i32_e32 v1, 6, v0
	s_add_u32 s2, s23, s4
	v_and_b32_e32 v164, 31, v0
	v_lshlrev_b32_e32 v148, 5, v1
	s_addc_u32 s5, s25, s5
	s_lshl_b32 s38, s18, 7
	s_lshl_b32 s37, s18, 8
	v_or_b32_e32 v2, v148, v164
	s_add_u32 s4, s2, s37
	v_ashrrev_i32_e32 v3, 31, v2
	s_addc_u32 s5, s5, 0
	v_lshlrev_b64 v[2:3], 11, v[2:3]
	v_lshl_add_u64 v[2:3], s[4:5], 0, v[2:3]
	s_lshl_b64 s[6:7], s[34:35], 10
	s_lshl_b64 s[4:5], s[34:35], 11
	s_add_u32 s2, s40, s4
	v_ashrrev_i32_e32 v80, 4, v0
	s_addc_u32 s18, s41, s5
	v_lshlrev_b32_e32 v34, 3, v0
	v_ashrrev_i32_e32 v81, 31, v80
	s_add_u32 s34, s2, s37
	v_and_b32_e32 v72, 0x78, v34
	v_lshlrev_b64 v[34:35], 11, v[80:81]
	s_addc_u32 s35, s18, 0
	v_bfe_u32 v165, v0, 5, 1
	v_mov_b32_e32 v75, v147
	v_lshlrev_b32_e32 v74, 1, v72
	v_lshl_add_u64 v[36:37], s[34:35], 0, v[34:35]
	v_lshlrev_b32_e32 v146, 4, v165
	v_lshl_add_u64 v[36:37], v[36:37], 0, v[74:75]
	v_lshl_add_u64 v[30:31], v[2:3], 0, v[146:147]
	v_add_co_u32_e32 v38, vcc, s66, v36
	global_load_dwordx4 v[2:5], v[30:31], off
	global_load_dwordx4 v[6:9], v[30:31], off offset:32
	global_load_dwordx4 v[10:13], v[30:31], off offset:64
	global_load_dwordx4 v[14:17], v[30:31], off offset:96
	global_load_dwordx4 v[18:21], v[30:31], off offset:128
	global_load_dwordx4 v[22:25], v[30:31], off offset:160
	global_load_dwordx4 v[26:29], v[30:31], off offset:192
	s_nop 0
	global_load_dwordx4 v[30:33], v[30:31], off offset:224
	v_addc_co_u32_e32 v39, vcc, 0, v37, vcc
	global_load_dwordx4 v[128:131], v[36:37], off
	global_load_dwordx4 v[132:135], v[38:39], off
	v_lshlrev_b32_e32 v36, 4, v0
	v_lshl_add_u32 v1, v1, 13, 0
	v_lshlrev_b32_e32 v38, 8, v164
	v_and_b32_e32 v75, 63, v0
	v_and_b32_e32 v37, 0xf0, v0
	v_and_b32_e32 v39, 0xf0, v36
	v_bitop3_b32 v40, v165, v0, 15 bitop3:0x78
	v_add_u32_e32 v42, v1, v38
	v_and_b32_e32 v0, 15, v0
	v_add_u32_e32 v86, 32, v80
	v_bitop3_b32 v90, v146, v39, 32 bitop3:0x36
	v_bitop3_b32 v91, v146, v39, 64 bitop3:0x36
	v_bitop3_b32 v92, v146, v39, s62 bitop3:0x36
	v_bitop3_b32 v93, v146, v39, s55 bitop3:0x36
	v_bitop3_b32 v94, v146, v39, s63 bitop3:0x36
	v_bitop3_b32 v95, v146, v39, s64 bitop3:0x36
	v_bitop3_b32 v96, v146, v39, s65 bitop3:0x36
	v_add_u32_e32 v89, s36, v148
	v_bitop3_b32 v98, v146, v36, s61 bitop3:0x78
	v_lshl_add_u32 v36, v40, 4, v42
	v_lshl_add_u64 v[78:79], s[4:5], 0, v[34:35]
	v_lshlrev_b32_e32 v0, 4, v0
	v_lshlrev_b32_e32 v41, 8, v80
	v_lshlrev_b32_e32 v39, 8, v86
	v_add_u32_e32 v40, v42, v90
	v_add_u32_e32 v43, v42, v91
	v_add_u32_e32 v44, v42, v92
	v_add_u32_e32 v45, v42, v93
	v_add_u32_e32 v46, v42, v94
	v_add_u32_e32 v47, v42, v95
	v_add_u32_e32 v42, v42, v96
	v_xad_u32 v37, v74, v37, 0
	v_add_u32_e32 v48, v1, v98
	v_add_u32_e32 v49, v1, v93
	v_lshlrev_b32_e32 v73, 2, v165
	s_lshl_b32 s18, s48, 6
	v_or3_b32 v78, v78, s37, v0
	v_mov_b32_e32 v82, 0
	s_mov_b32 s2, 0
	v_lshlrev_b64 v[76:77], 10, v[80:81]
	v_add_u32_e32 v97, 0, v38
	s_add_i32 s18, s18, 64
	v_sub_u32_e32 v173, 0, v89
	v_lshl_add_u64 v[84:85], s[20:21], 0, v[78:79]
	v_mov_b32_e32 v81, 0xf149f2ca
	v_add_u32_e32 v174, v37, v41
	v_add_u32_e32 v175, v37, v39
	v_readfirstlane_b32 s91, v173
	v_add_u32_e32 v172, v48, v38
	v_add_u32_e32 v171, v49, v38
	s_waitcnt vmcnt(9)
	ds_write_b128 v36, v[2:5] offset:36864
	s_waitcnt vmcnt(8)
	ds_write_b128 v40, v[6:9] offset:36864
	s_waitcnt vmcnt(7)
	ds_write_b128 v43, v[10:13] offset:36864
	s_waitcnt vmcnt(6)
	ds_write_b128 v44, v[14:17] offset:36864
	s_waitcnt vmcnt(5)
	ds_write_b128 v45, v[18:21] offset:36864
	s_waitcnt vmcnt(4)
	ds_write_b128 v46, v[22:25] offset:36864
	s_waitcnt vmcnt(3)
	ds_write_b128 v47, v[26:29] offset:36864
	s_waitcnt vmcnt(2)
	ds_write_b128 v42, v[30:33] offset:36864
	v_add_u32_e32 v2, v1, v90
	v_add_u32_e32 v3, v1, v94
	v_add_u32_e32 v4, v1, v91
	v_add_u32_e32 v5, v1, v95
	v_add_u32_e32 v6, v1, v92
	v_add_u32_e32 v1, v1, v96
	v_or_b32_e32 v7, v89, v164
	s_waitcnt vmcnt(1)
	v_mov_b64_e32 v[64:65], v[128:129]
	s_waitcnt vmcnt(0)
	v_mov_b64_e32 v[68:69], v[132:133]
	v_sub_u32_e32 v88, v73, v7
	v_add_u32_e32 v170, v2, v38
	v_add_u32_e32 v169, v3, v38
	v_add_u32_e32 v168, v4, v38
	v_add_u32_e32 v167, v5, v38
	v_add_u32_e32 v166, v6, v38
	v_add_u32_e32 v149, v1, v38
	v_mov_b64_e32 v[66:67], v[130:131]
	v_mov_b64_e32 v[70:71], v[134:135]
	v_mov_b32_e32 v87, 0xf149f2ca
	v_mov_b32_e32 v83, v82
	s_waitcnt lgkmcnt(0)
	s_barrier
	ds_read_b32 v252, v147 offset:32768
	ds_read_b32 v253, v147 offset:33792
	s_waitcnt lgkmcnt(0)
	v_add_u32_e32 v177, v97, v93
	v_add_u32_e32 v178, v97, v90
	v_add_u32_e32 v179, v97, v94
	v_add_u32_e32 v180, v97, v91
	v_add_u32_e32 v181, v97, v95
	v_add_u32_e32 v182, v97, v92
	v_add_u32_e32 v183, v97, v96
	s_branch .LBB0_276

; #define SBAR() __builtin_amdgcn_sched_barrier(0)
; #define KLOAD(t) do { const bf16* kp_ = Kb + (size_t)((t) * 64 + sr) * 1024 + sc; ks0 = *reinterpret_cast<const bf16x8*>(kp_); ks1 = *reinterpret_cast<const bf16x8*>(kp_ + 32 * 1024); } while (0)
; #define KWRITE() do { *reinterpret_cast<bf16x8*>(K_lds + kst0) = ks0; *reinterpret_cast<bf16x8*>(K_lds + kst1) = ks1; } while (0)
; template <bool DIFF> ...
;     ...
;   if (DIFF) {
;   KLOAD(t_lo);
;   for (int t = t_lo; t < t_hi; ++t) {
;     __syncthreads();
;     KWRITE();
;     __syncthreads();
;     if (t + 1 < t_hi) KLOAD(t + 1);
;     const bool active = DIFF || (t >= rstart && t < rstart + 8);
;     if (active) {
;       f32x16 a0, b0, a1, b1;
;       qkt<DIFF>(a0, b0, K_lds, Q_lds, r32, r32, hi);
;       qkt<DIFF>(a1, b1, K_lds, Q_lds, r32 + 32, r32, hi);
;       SBAR();
;       float cb0, cb1;
;       BIAS_APPLY(t, 0, a0, b0, cb0);
.LBB0_276:
	v_add_u32_e32 v176, v97, v98
	s_waitcnt lgkmcnt(0)
	s_mov_b32 s94, 0
	s_add_i32 s92, s2, s91
	s_cmpk_ge_i32 s92, 0x9f
	s_cbranch_scc1 .Lsw1p_hi
	s_cmpk_le_i32 s92, 0xff41
	s_cbranch_scc0 .Lsw1p_go
	v_mov_b32_e32 v235, v252
	v_mov_b32_e32 v241, v252
	s_mov_b32 s94, 1
	s_branch .Lsw1p_go
.Lsw1p_hi:
	v_mov_b32_e32 v235, v253
	v_mov_b32_e32 v241, v253
	s_mov_b32 s94, 1
.Lsw1p_go:
	s_barrier
	s_waitcnt vmcnt(0)
	ds_write_b128 v174, v[64:67]
	ds_write_b128 v175, v[68:71]
	s_waitcnt lgkmcnt(0)
	s_barrier
	s_cmp_lg_u32 s94, 0
	s_cbranch_scc1 .Lsw1f
	ds_read_b128 v[0:3], v176
	ds_read_b128 v[4:7], v172 offset:36864
	v_add_u32_e32 v177, v97, v93
	ds_read_b128 v[8:11], v177
	ds_read_b128 v[12:15], v176 offset:8192
	s_waitcnt lgkmcnt(2)
	v_mfma_f32_32x32x16_bf16 v[48:63], v[0:3], v[4:7], 0
	ds_read_b128 v[0:3], v171 offset:36864
	ds_read_b128 v[64:67], v177 offset:8192
	v_add_u32_e32 v178, v97, v90
	v_add_u32_e32 v179, v97, v94
	v_add_u32_e32 v180, v97, v91
	v_add_u32_e32 v181, v97, v95
	v_add_u32_e32 v182, v97, v92
	v_add_u32_e32 v183, v97, v96
	s_waitcnt lgkmcnt(1)
	v_mfma_f32_32x32x16_bf16 v[32:47], v[8:11], v[0:3], 0
	ds_read_b128 v[8:11], v178
	ds_read_b128 v[68:71], v170 offset:36864
	ds_read_b128 v[16:19], v179
	ds_read_b128 v[100:103], v178 offset:8192
	ds_read_b128 v[104:107], v169 offset:36864
	ds_read_b128 v[108:111], v179 offset:8192
	s_waitcnt lgkmcnt(1)
	v_mfma_f32_32x32x16_bf16 v[32:47], v[16:19], v[104:107], v[32:47]
	v_mfma_f32_32x32x16_bf16 v[48:63], v[8:11], v[68:71], v[48:63]
	ds_read_b128 v[8:11], v180
	ds_read_b128 v[112:115], v168 offset:36864
	ds_read_b128 v[16:19], v181
	ds_read_b128 v[116:119], v180 offset:8192
	ds_read_b128 v[120:123], v167 offset:36864
	ds_read_b128 v[124:127], v181 offset:8192
	s_waitcnt lgkmcnt(1)
	v_mfma_f32_32x32x16_bf16 v[32:47], v[16:19], v[120:123], v[32:47]
	v_mfma_f32_32x32x16_bf16 v[48:63], v[8:11], v[112:115], v[48:63]
	ds_read_b128 v[8:11], v182
	ds_read_b128 v[136:139], v166 offset:36864
	ds_read_b128 v[16:19], v183
	ds_read_b128 v[140:143], v182 offset:8192
	ds_read_b128 v[150:153], v149 offset:36864
	ds_read_b128 v[184:187], v183 offset:8192
	s_waitcnt lgkmcnt(1)
	v_mfma_f32_32x32x16_bf16 v[32:47], v[16:19], v[150:153], v[32:47]
	v_mfma_f32_32x32x16_bf16 v[16:31], v[12:15], v[4:7], 0
	v_mfma_f32_32x32x16_bf16 v[16:31], v[100:103], v[68:71], v[16:31]
	v_add_co_u32_e32 v68, vcc, s66, v84
	s_nop 1
	v_addc_co_u32_e32 v69, vcc, 0, v85, vcc
	global_load_dwordx4 v[68:71], v[68:69], off
	v_mfma_f32_32x32x16_bf16 v[48:63], v[8:11], v[136:139], v[48:63]
	v_mfma_f32_32x32x16_bf16 v[0:15], v[64:67], v[0:3], 0
	global_load_dwordx4 v[64:67], v[84:85], off
	v_mfma_f32_32x32x16_bf16 v[0:15], v[108:111], v[104:107], v[0:15]
	v_mfma_f32_32x32x16_bf16 v[16:31], v[116:119], v[112:115], v[16:31]
	v_mfma_f32_32x32x16_bf16 v[0:15], v[124:127], v[120:123], v[0:15]
	v_mfma_f32_32x32x16_bf16 v[16:31], v[140:143], v[136:139], v[16:31]
	s_waitcnt lgkmcnt(0)
	v_mfma_f32_32x32x16_bf16 v[0:15], v[184:187], v[150:153], v[0:15]
	s_add_i32 s92, s2, s91
	s_cmpk_ge_i32 s92, 0x9f
	s_cbranch_scc1 .Lb1a_hi
	s_cmpk_le_i32 s92, 0xff41
	s_cbranch_scc1 .Lb1a_lo
	v_add_u32_e32 v99, s2, v88
	v_add_u32_e32 v99, 0x80, v99
	v_med3_i32 v100, v99, 0, v163
	v_lshl_add_u32 v103, v100, 2, 0
	v_max_i32_e32 v100, -1, v99
	v_add_u32_e32 v100, 1, v100
	v_min_u32_e32 v100, 0x100, v100
	v_lshl_add_u32 v111, v100, 2, 0
	v_max_i32_e32 v100, -2, v99
	v_add_u32_e32 v100, 2, v100
	v_min_u32_e32 v100, 0x100, v100
	v_lshl_add_u32 v112, v100, 2, 0
	v_max_i32_e32 v100, -3, v99
	v_add_u32_e32 v100, 3, v100
	v_min_u32_e32 v100, 0x100, v100
	v_lshl_add_u32 v113, v100, 2, 0
	v_max_i32_e32 v100, -8, v99
	v_add_u32_e32 v100, 8, v100
	v_min_u32_e32 v100, 0x100, v100
	v_lshl_add_u32 v114, v100, 2, 0
	v_max_i32_e32 v100, -9, v99
	v_add_u32_e32 v100, 9, v100
	v_min_u32_e32 v100, 0x100, v100
	v_lshl_add_u32 v115, v100, 2, 0
	v_max_i32_e32 v100, -10, v99
	v_add_u32_e32 v100, 10, v100
	v_min_u32_e32 v100, 0x100, v100
	v_lshl_add_u32 v116, v100, 2, 0
	v_max_i32_e32 v100, -11, v99
	v_add_u32_e32 v100, 11, v100
	v_min_u32_e32 v100, 0x100, v100
	v_lshl_add_u32 v117, v100, 2, 0
	v_max_i32_e32 v100, -16, v99
	v_max_i32_e32 v101, 0xffffffef, v99
	v_max_i32_e32 v104, 0xffffffee, v99
	v_max_i32_e32 v105, 0xffffffed, v99
	v_max_i32_e32 v106, 0xffffffe8, v99
	v_max_i32_e32 v107, 0xffffffe7, v99
	v_max_i32_e32 v108, 0xffffffe6, v99
	v_add_u32_e32 v100, 16, v100
	v_add_u32_e32 v101, 17, v101
	v_add_u32_e32 v104, 18, v104
	v_add_u32_e32 v105, 19, v105
	v_add_u32_e32 v106, 24, v106
	v_add_u32_e32 v107, 25, v107
	v_add_u32_e32 v108, 26, v108
	v_max_i32_e32 v99, 0xffffffe5, v99
	v_min_u32_e32 v100, 0x100, v100
	v_min_u32_e32 v101, 0x100, v101
	v_min_u32_e32 v104, 0x100, v104
	v_min_u32_e32 v105, 0x100, v105
	v_min_u32_e32 v106, 0x100, v106
	v_min_u32_e32 v107, 0x100, v107
	v_min_u32_e32 v108, 0x100, v108
	v_add_u32_e32 v99, 27, v99
	v_lshl_add_u32 v100, v100, 2, 0
	v_lshl_add_u32 v101, v101, 2, 0
	v_lshl_add_u32 v104, v104, 2, 0
	v_lshl_add_u32 v105, v105, 2, 0
	v_lshl_add_u32 v106, v106, 2, 0
	v_lshl_add_u32 v107, v107, 2, 0
	v_lshl_add_u32 v108, v108, 2, 0
	v_min_u32_e32 v99, 0x100, v99
	v_lshl_add_u32 v99, v99, 2, 0
	ds_read_b32 v100, v100 offset:32768
	ds_read_b32 v101, v101 offset:32768
	ds_read_b32 v104, v104 offset:32768
	ds_read_b32 v105, v105 offset:32768
	ds_read_b32 v106, v106 offset:32768
	ds_read_b32 v107, v107 offset:32768
	ds_read_b32 v108, v108 offset:32768
	ds_read_b32 v109, v99 offset:32768
	ds_read_b32 v110, v103 offset:32768
	ds_read_b32 v111, v111 offset:32768
	ds_read_b32 v112, v112 offset:32768
	ds_read_b32 v113, v113 offset:32768
	ds_read_b32 v114, v114 offset:32768
	ds_read_b32 v115, v115 offset:32768
	ds_read_b32 v116, v116 offset:32768
	ds_read_b32 v117, v117 offset:32768
	s_waitcnt lgkmcnt(8)
	v_pk_add_f32 v[62:63], v[62:63], v[108:109]
	v_pk_add_f32 v[60:61], v[60:61], v[106:107]
	v_pk_add_f32 v[58:59], v[58:59], v[104:105]
	v_pk_add_f32 v[56:57], v[56:57], v[100:101]
	s_waitcnt lgkmcnt(0)
	v_pk_add_f32 v[54:55], v[54:55], v[116:117]
	v_pk_add_f32 v[52:53], v[52:53], v[114:115]
	v_pk_add_f32 v[50:51], v[50:51], v[112:113]
	v_pk_add_f32 v[48:49], v[48:49], v[110:111]
	v_pk_add_f32 v[46:47], v[46:47], v[108:109]
	v_pk_add_f32 v[44:45], v[44:45], v[106:107]
	v_pk_add_f32 v[42:43], v[42:43], v[104:105]
	v_pk_add_f32 v[40:41], v[40:41], v[100:101]
	v_pk_add_f32 v[38:39], v[38:39], v[116:117]
	v_pk_add_f32 v[36:37], v[36:37], v[114:115]
	v_pk_add_f32 v[34:35], v[34:35], v[112:113]
	v_pk_add_f32 v[32:33], v[32:33], v[110:111]
	v_mov_b32_e32 v99, 0
	s_branch .LBB0_284

; template <bool DIFF>
; __device__ __forceinline__ void qkt(f32x16& a, f32x16& b, const char* Ks, const char* Qs, int krow, int r32, int hi) {
;   a = f32x16{}; b = f32x16{};
; #pragma unroll
;   for (int d = 0; d < 4; ++d) {
;     const int cb0 = (d * 16 + hi * 8) * 2, cb1 = ((d + 4) * 16 + hi * 8) * 2;
;     const bf16x8 k0 = *reinterpret_cast<const bf16x8*>(Ks + KSWZ(krow, cb0)), q0 = *reinterpret_cast<const bf16x8*>(Qs + KSWZ(r32, cb0));
;     const bf16x8 k1 = *reinterpret_cast<const bf16x8*>(Ks + KSWZ(krow, cb1)), q1 = *reinterpret_cast<const bf16x8*>(Qs + KSWZ(r32, cb1));
;     a = __builtin_amdgcn_mfma_f32_32x32x16_bf16(k0, q0, a, 0, 0, 0);
;     b = __builtin_amdgcn_mfma_f32_32x32x16_bf16(k1, q1, b, 0, 0, 0); }
.Lsw1f:
	ds_read_b128 v[0:3], v176
	ds_read_b128 v[4:7], v172 offset:36864

; template <bool DIFF>
; __device__ __forceinline__ void qkt(f32x16& a, f32x16& b, const char* Ks, const char* Qs, int krow, int r32, int hi) {
;   a = f32x16{}; b = f32x16{};
; #pragma unroll
;   for (int d = 0; d < 4; ++d) {
;     const int cb0 = (d * 16 + hi * 8) * 2, cb1 = ((d + 4) * 16 + hi * 8) * 2;
;     const bf16x8 k0 = *reinterpret_cast<const bf16x8*>(Ks + KSWZ(krow, cb0)), q0 = *reinterpret_cast<const bf16x8*>(Qs + KSWZ(r32, cb0));
;     const bf16x8 k1 = *reinterpret_cast<const bf16x8*>(Ks + KSWZ(krow, cb1)), q1 = *reinterpret_cast<const bf16x8*>(Qs + KSWZ(r32, cb1));
;     a = __builtin_amdgcn_mfma_f32_32x32x16_bf16(k0, q0, a, 0, 0, 0);
;     b = __builtin_amdgcn_mfma_f32_32x32x16_bf16(k1, q1, b, 0, 0, 0); }
	ds_read_b128 v[8:11], v177
	ds_read_b128 v[12:15], v176 offset:8192
	s_waitcnt lgkmcnt(2)
	v_mfma_f32_32x32x16_bf16 v[48:63], v[0:3], v[4:7], 0
	ds_read_b128 v[0:3], v171 offset:36864
	ds_read_b128 v[64:67], v177 offset:8192


; template <bool DIFF>
; __device__ __forceinline__ void qkt(f32x16& a, f32x16& b, const char* Ks, const char* Qs, int krow, int r32, int hi) {
;   a = f32x16{}; b = f32x16{};
; #pragma unroll
;   for (int d = 0; d < 4; ++d) {
;     const int cb0 = (d * 16 + hi * 8) * 2, cb1 = ((d + 4) * 16 + hi * 8) * 2;
;     const bf16x8 k0 = *reinterpret_cast<const bf16x8*>(Ks + KSWZ(krow, cb0)), q0 = *reinterpret_cast<const bf16x8*>(Qs + KSWZ(r32, cb0));
;     const bf16x8 k1 = *reinterpret_cast<const bf16x8*>(Ks + KSWZ(krow, cb1)), q1 = *reinterpret_cast<const bf16x8*>(Qs + KSWZ(r32, cb1));
;     a = __builtin_amdgcn_mfma_f32_32x32x16_bf16(k0, q0, a, 0, 0, 0);
;     b = __builtin_amdgcn_mfma_f32_32x32x16_bf16(k1, q1, b, 0, 0, 0); }
;   if (!DIFF) {
; #pragma unroll
;     for (int r = 0; r < 16; ++r) a[r] += b[r]; }
; }
; __device__ __forceinline__ void stat_upd(const f32x16& p0, float& m, float& l, const float C, const float cb) {
;   float mx = p0[0];
; #pragma unroll
;   for (int r = 1; r < 16; ++r) mx = fmaxf(mx, p0[r]);
;   { auto rr = __builtin_amdgcn_permlane32_swap(__float_as_uint(mx), __float_as_uint(mx), false, false);
;     mx = fmaxf(__uint_as_float(rr[0]), __uint_as_float(rr[1])); }
;   mx += cb;
;   const float mn = fmaxf(m, mx), alpha = __builtin_amdgcn_exp2f((m - mn) * C), mnC = (cb - mn) * C; float s = 0.f;
; #pragma unroll
;   for (int r = 0; r < 16; ++r) s += __builtin_amdgcn_exp2f(fmaf(p0[r], C, mnC));
;   l = l * alpha + s; m = mn;
; }
	s_waitcnt lgkmcnt(1)
	v_mfma_f32_32x32x16_bf16 v[32:47], v[8:11], v[0:3], 0
	ds_read_b128 v[8:11], v178
	ds_read_b128 v[68:71], v170 offset:36864
	ds_read_b128 v[16:19], v179
	ds_read_b128 v[100:103], v178 offset:8192
	ds_read_b128 v[104:107], v169 offset:36864
	ds_read_b128 v[108:111], v179 offset:8192
	s_waitcnt lgkmcnt(1)
	v_mfma_f32_32x32x16_bf16 v[32:47], v[16:19], v[104:107], v[32:47]
	v_mfma_f32_32x32x16_bf16 v[48:63], v[8:11], v[68:71], v[48:63]
	ds_read_b128 v[8:11], v180
	ds_read_b128 v[112:115], v168 offset:36864
	ds_read_b128 v[16:19], v181
	ds_read_b128 v[116:119], v180 offset:8192
	ds_read_b128 v[120:123], v167 offset:36864
	ds_read_b128 v[124:127], v181 offset:8192
	s_waitcnt lgkmcnt(1)
	v_mfma_f32_32x32x16_bf16 v[32:47], v[16:19], v[120:123], v[32:47]
	v_mfma_f32_32x32x16_bf16 v[48:63], v[8:11], v[112:115], v[48:63]
	ds_read_b128 v[8:11], v182
	ds_read_b128 v[136:139], v166 offset:36864
	ds_read_b128 v[16:19], v183
	ds_read_b128 v[140:143], v182 offset:8192
	ds_read_b128 v[150:153], v149 offset:36864
	ds_read_b128 v[184:187], v183 offset:8192
	s_waitcnt lgkmcnt(1)
	v_mfma_f32_32x32x16_bf16 v[32:47], v[16:19], v[150:153], v[32:47]
	v_mfma_f32_32x32x16_bf16 v[48:63], v[8:11], v[136:139], v[48:63]
	s_waitcnt lgkmcnt(0)
	v_mfma_f32_32x32x16_bf16 v[16:31], v[12:15], v[4:7], 0
	s_nop 10
	v_max_f32_e32 v236, v49, v49
	v_max_f32_e32 v237, v48, v48
	v_max_f32_e32 v236, v237, v236
	v_max3_f32 v236, v236, v50, v51
	v_max3_f32 v236, v236, v52, v53
	v_max3_f32 v236, v236, v54, v55
	v_max3_f32 v236, v236, v56, v57
	v_max3_f32 v236, v236, v58, v59
	v_max3_f32 v236, v236, v60, v61
	v_max3_f32 v239, v236, v62, v63
	v_max_f32_e32 v236, v33, v33
	v_mfma_f32_32x32x16_bf16 v[16:31], v[100:103], v[68:71], v[16:31]
	v_max_f32_e32 v237, v32, v32
	v_max_f32_e32 v236, v237, v236
	v_max3_f32 v236, v236, v34, v35
	v_max3_f32 v236, v236, v36, v37
	v_max3_f32 v236, v236, v38, v39
	v_max3_f32 v236, v236, v40, v41
	v_max3_f32 v236, v236, v42, v43
	v_max3_f32 v236, v236, v44, v45
	v_max3_f32 v236, v236, v46, v47
	v_mov_b32_e32 v240, v239
	v_mov_b32_e32 v237, v236
	s_nop 0
	v_permlane32_swap_b32_e32 v239, v240
	v_permlane32_swap_b32_e32 v236, v237
	v_max_f32_e32 v238, v239, v239
	v_mfma_f32_32x32x16_bf16 v[0:15], v[64:67], v[0:3], 0
	v_add_co_u32_e32 v68, vcc, s66, v84
	s_nop 1
	v_addc_co_u32_e32 v69, vcc, 0, v85, vcc
	global_load_dwordx4 v[68:71], v[68:69], off
	global_load_dwordx4 v[64:67], v[84:85], off
	v_max_f32_e32 v239, v240, v240
	v_max_f32_e32 v238, v238, v239
	s_waitcnt lgkmcnt(0)
	v_add_f32_e32 v238, v235, v238
	v_max_f32_e32 v239, v87, v87
	v_max_f32_e32 v240, v239, v238
	v_sub_f32_e32 v238, v235, v240
	v_mul_f32_e32 v238, 0x3e38aa3b, v238
	v_fmamk_f32 v48, v48, 0x3e38aa3b, v238
	v_exp_f32_e32 v48, v48
	v_fmamk_f32 v49, v49, 0x3e38aa3b, v238
	v_exp_f32_e32 v49, v49
	v_fmamk_f32 v50, v50, 0x3e38aa3b, v238
	v_mfma_f32_32x32x16_bf16 v[0:15], v[108:111], v[104:107], v[0:15]
	v_exp_f32_e32 v50, v50
	v_fmamk_f32 v51, v51, 0x3e38aa3b, v238
	v_exp_f32_e32 v51, v51
	v_add_f32_e32 v48, 0, v48
	v_add_f32_e32 v48, v49, v48
	v_fmamk_f32 v49, v52, 0x3e38aa3b, v238
	v_add_f32_e32 v48, v50, v48
	v_exp_f32_e32 v49, v49
	v_fmamk_f32 v50, v53, 0x3e38aa3b, v238
	v_add_f32_e32 v48, v51, v48
	v_exp_f32_e32 v50, v50
	v_mfma_f32_32x32x16_bf16 v[16:31], v[116:119], v[112:115], v[16:31]
	v_fmamk_f32 v51, v54, 0x3e38aa3b, v238
	v_exp_f32_e32 v51, v51
	v_fmamk_f32 v52, v55, 0x3e38aa3b, v238
	v_exp_f32_e32 v52, v52
	v_add_f32_e32 v48, v49, v48
	v_add_f32_e32 v48, v50, v48
	v_add_f32_e32 v48, v51, v48
	v_add_f32_e32 v49, v52, v48
	v_fmamk_f32 v48, v56, 0x3e38aa3b, v238
	v_exp_f32_e32 v51, v48
	v_fmamk_f32 v48, v57, 0x3e38aa3b, v238
	v_exp_f32_e32 v53, v48
	v_mfma_f32_32x32x16_bf16 v[0:15], v[124:127], v[120:123], v[0:15]
	v_fmamk_f32 v48, v58, 0x3e38aa3b, v238
	v_exp_f32_e32 v55, v48
	v_fmamk_f32 v48, v59, 0x3e38aa3b, v238
	v_exp_f32_e32 v57, v48
	v_fmamk_f32 v48, v60, 0x3e38aa3b, v238
	v_exp_f32_e32 v59, v48
	v_fmamk_f32 v48, v61, 0x3e38aa3b, v238
	v_exp_f32_e32 v61, v48
	v_fmamk_f32 v48, v62, 0x3e38aa3b, v238
	v_exp_f32_e32 v239, v48
	v_mfma_f32_32x32x16_bf16 v[16:31], v[140:143], v[136:139], v[16:31]
	v_sub_f32_e32 v48, v87, v240
	v_mul_f32_e32 v48, 0x3e38aa3b, v48
	v_exp_f32_e32 v243, v48
	v_max_f32_e32 v48, v236, v236
	v_max_f32_e32 v50, v237, v237
	v_max_f32_e32 v48, v48, v50
	v_add_f32_e32 v48, v235, v48
	v_max_f32_e32 v50, v81, v81
	v_max_f32_e32 v236, v50, v48
	v_sub_f32_e32 v48, v235, v236
	v_mul_f32_e32 v62, 0x3e38aa3b, v48
	v_fmamk_f32 v32, v32, 0x3e38aa3b, v62
	v_exp_f32_e32 v32, v32
	v_mfma_f32_32x32x16_bf16 v[0:15], v[184:187], v[150:153], v[0:15]
	v_fmamk_f32 v33, v33, 0x3e38aa3b, v62
	v_exp_f32_e32 v33, v33
	v_fmamk_f32 v34, v34, 0x3e38aa3b, v62
	v_exp_f32_e32 v34, v34
	v_fmamk_f32 v35, v35, 0x3e38aa3b, v62
	v_exp_f32_e32 v35, v35
	v_add_f32_e32 v32, 0, v32
	v_add_f32_e32 v32, v33, v32
	v_fmamk_f32 v33, v36, 0x3e38aa3b, v62
	v_add_f32_e32 v32, v34, v32
	v_exp_f32_e32 v33, v33
	v_fmamk_f32 v34, v37, 0x3e38aa3b, v62
	v_add_f32_e32 v32, v35, v32
	v_exp_f32_e32 v34, v34
	v_fmamk_f32 v35, v38, 0x3e38aa3b, v62
	v_exp_f32_e32 v35, v35
	v_add_f32_e32 v32, v33, v32
	v_add_f32_e32 v32, v34, v32
	v_max_f32_e32 v34, v17, v17
	v_add_f32_e32 v32, v35, v32
	v_max_f32_e32 v35, v16, v16
; #define SBAR() __builtin_amdgcn_sched_barrier(0)
; __device__ __forceinline__ void stat_upd(const f32x16& p0, float& m, float& l, const float C, const float cb) {
;   float mx = p0[0];
; #pragma unroll
;   for (int r = 1; r < 16; ++r) mx = fmaxf(mx, p0[r]);
;   { auto rr = __builtin_amdgcn_permlane32_swap(__float_as_uint(mx), __float_as_uint(mx), false, false);
;     mx = fmaxf(__uint_as_float(rr[0]), __uint_as_float(rr[1])); }
;   mx += cb;
;   const float mn = fmaxf(m, mx), alpha = __builtin_amdgcn_exp2f((m - mn) * C), mnC = (cb - mn) * C; float s = 0.f;
; #pragma unroll
;   for (int r = 0; r < 16; ++r) s += __builtin_amdgcn_exp2f(fmaf(p0[r], C, mnC));
;   l = l * alpha + s; m = mn;
; }
; template <bool DIFF> ...
;     ...
;       stat_upd(a0, m1, l1, C, cb0);
;       if (DIFF) stat_upd(b0, m2, l2, C, cb0);
;       SBAR();
;       BIAS_APPLY(t, 1, a1, b1, cb1);
;       stat_upd(a1, m1, l1, C, cb1);
;       if (DIFF) stat_upd(b1, m2, l2, C, cb1);
;     }
;   }
	v_fmamk_f32 v36, v39, 0x3e38aa3b, v62
	v_max_f32_e32 v34, v35, v34
	v_exp_f32_e32 v36, v36
	v_max3_f32 v34, v34, v18, v19
	v_max3_f32 v34, v34, v20, v21
	v_max3_f32 v34, v34, v22, v23
	v_max3_f32 v34, v34, v24, v25
	v_add_f32_e32 v48, v36, v32
	v_fmamk_f32 v32, v40, 0x3e38aa3b, v62
	v_max3_f32 v34, v34, v26, v27
	v_exp_f32_e32 v50, v32
	v_fmamk_f32 v32, v41, 0x3e38aa3b, v62
	v_max3_f32 v34, v34, v28, v29
	v_exp_f32_e32 v52, v32
	v_fmamk_f32 v32, v42, 0x3e38aa3b, v62
	v_max3_f32 v34, v34, v30, v31
	v_exp_f32_e32 v54, v32
	v_fmamk_f32 v32, v43, 0x3e38aa3b, v62
	v_mov_b32_e32 v35, v34
	v_exp_f32_e32 v56, v32
	v_fmamk_f32 v32, v44, 0x3e38aa3b, v62
	v_permlane32_swap_b32_e32 v34, v35
	v_exp_f32_e32 v58, v32
	v_fmamk_f32 v32, v45, 0x3e38aa3b, v62
	v_max_f32_e32 v35, v35, v35
	v_max_f32_e32 v34, v34, v34
	v_fmac_f32_e32 v238, 0x3e38aa3b, v63
	v_exp_f32_e32 v60, v32
	v_fmamk_f32 v32, v46, 0x3e38aa3b, v62
	v_max_f32_e32 v34, v34, v35
	v_exp_f32_e32 v63, v238
	v_exp_f32_e32 v238, v32
	v_sub_f32_e32 v32, v81, v236
	v_add_f32_e32 v34, v241, v34
	v_mul_f32_e32 v32, 0x3e38aa3b, v32
	v_max_f32_e32 v87, v240, v34
	v_exp_f32_e32 v242, v32
	v_pk_add_f32 v[32:33], v[50:51], v[48:49]
	v_sub_f32_e32 v34, v241, v87
	v_pk_add_f32 v[32:33], v[52:53], v[32:33]
	v_mul_f32_e32 v34, 0x3e38aa3b, v34
	v_fmac_f32_e32 v62, 0x3e38aa3b, v47
	v_pk_add_f32 v[32:33], v[54:55], v[32:33]
	v_fmamk_f32 v16, v16, 0x3e38aa3b, v34
	v_exp_f32_e32 v62, v62
	v_pk_add_f32 v[32:33], v[56:57], v[32:33]
	v_exp_f32_e32 v35, v16
	v_fmamk_f32 v16, v17, 0x3e38aa3b, v34
	v_pk_add_f32 v[32:33], v[58:59], v[32:33]
	v_exp_f32_e32 v36, v16
	v_fmamk_f32 v18, v18, 0x3e38aa3b, v34
	v_pk_add_f32 v[32:33], v[60:61], v[32:33]
	v_exp_f32_e32 v18, v18
	v_fmamk_f32 v19, v19, 0x3e38aa3b, v34
	v_pk_add_f32 v[32:33], v[238:239], v[32:33]
	v_exp_f32_e32 v19, v19
	v_fmamk_f32 v20, v20, 0x3e38aa3b, v34
	v_pk_add_f32 v[16:17], v[62:63], v[32:33]
	v_add_f32_e32 v32, 0, v35
	v_exp_f32_e32 v20, v20
	v_fmamk_f32 v21, v21, 0x3e38aa3b, v34
	v_add_f32_e32 v32, v36, v32
	v_exp_f32_e32 v21, v21
	v_add_f32_e32 v18, v18, v32
	v_add_f32_e32 v18, v19, v18
	v_add_f32_e32 v18, v20, v18
	v_add_f32_e32 v19, v21, v18
	v_fmamk_f32 v18, v22, 0x3e38aa3b, v34
	v_max_f32_e32 v20, v1, v1
	v_max_f32_e32 v22, v0, v0
	v_max_f32_e32 v20, v22, v20
	v_max3_f32 v20, v20, v2, v3
	v_max3_f32 v20, v20, v4, v5
	v_max3_f32 v20, v20, v6, v7
	v_max3_f32 v20, v20, v8, v9
	v_max3_f32 v20, v20, v10, v11
	v_max3_f32 v20, v20, v12, v13
	v_max3_f32 v20, v20, v14, v15
	v_exp_f32_e32 v21, v18
	v_fmamk_f32 v18, v23, 0x3e38aa3b, v34
	v_mov_b32_e32 v22, v20
	v_exp_f32_e32 v23, v18
	v_fmamk_f32 v18, v24, 0x3e38aa3b, v34
	v_permlane32_swap_b32_e32 v20, v22
	v_exp_f32_e32 v33, v18
	v_fmamk_f32 v18, v25, 0x3e38aa3b, v34
	v_max_f32_e32 v22, v22, v22
	v_max_f32_e32 v20, v20, v20
	v_exp_f32_e32 v25, v18
	v_fmamk_f32 v18, v26, 0x3e38aa3b, v34
	v_max_f32_e32 v20, v20, v22
	v_exp_f32_e32 v35, v18
	v_fmamk_f32 v18, v27, 0x3e38aa3b, v34
	v_add_f32_e32 v20, v241, v20
	v_exp_f32_e32 v27, v18
	v_fmamk_f32 v18, v28, 0x3e38aa3b, v34
	v_max_f32_e32 v81, v236, v20
	v_exp_f32_e32 v37, v18
	v_fmamk_f32 v18, v29, 0x3e38aa3b, v34
	v_sub_f32_e32 v20, v241, v81
	v_exp_f32_e32 v29, v18
	v_fmamk_f32 v18, v30, 0x3e38aa3b, v34
	v_mul_f32_e32 v30, 0x3e38aa3b, v20
	v_fmamk_f32 v0, v0, 0x3e38aa3b, v30
	v_exp_f32_e32 v0, v0
	v_fmamk_f32 v1, v1, 0x3e38aa3b, v30
	v_exp_f32_e32 v20, v1
	v_fmamk_f32 v2, v2, 0x3e38aa3b, v30
	v_exp_f32_e32 v2, v2
	v_fmamk_f32 v3, v3, 0x3e38aa3b, v30
	v_exp_f32_e32 v3, v3
	v_fmamk_f32 v4, v4, 0x3e38aa3b, v30
	v_add_f32_e32 v0, 0, v0
	v_exp_f32_e32 v4, v4
	v_fmamk_f32 v5, v5, 0x3e38aa3b, v30
	v_add_f32_e32 v0, v20, v0
	v_exp_f32_e32 v5, v5
	v_add_f32_e32 v0, v2, v0
	v_add_f32_e32 v0, v3, v0
	v_exp_f32_e32 v39, v18
	v_sub_f32_e32 v18, v240, v87
	v_add_f32_e32 v0, v4, v0
	v_mul_f32_e32 v1, 0x3e38aa3b, v18
	v_add_f32_e32 v18, v5, v0
	v_fmamk_f32 v0, v6, 0x3e38aa3b, v30
	v_exp_f32_e32 v20, v0
	v_fmamk_f32 v0, v7, 0x3e38aa3b, v30
	v_exp_f32_e32 v22, v0
	v_fmamk_f32 v0, v8, 0x3e38aa3b, v30
	v_exp_f32_e32 v32, v0
	v_fmamk_f32 v0, v9, 0x3e38aa3b, v30
	v_fmac_f32_e32 v34, 0x3e38aa3b, v31
	v_exp_f32_e32 v24, v0
	v_fmamk_f32 v0, v10, 0x3e38aa3b, v30
	v_exp_f32_e32 v31, v34
	v_exp_f32_e32 v34, v0
	v_fmamk_f32 v0, v11, 0x3e38aa3b, v30
	v_pk_add_f32 v[2:3], v[20:21], v[18:19]
	v_exp_f32_e32 v26, v0
	v_fmamk_f32 v0, v12, 0x3e38aa3b, v30
	v_pk_add_f32 v[2:3], v[22:23], v[2:3]
	v_exp_f32_e32 v36, v0
	v_fmamk_f32 v0, v13, 0x3e38aa3b, v30
	v_pk_add_f32 v[2:3], v[32:33], v[2:3]
	v_exp_f32_e32 v28, v0
	v_fmamk_f32 v0, v14, 0x3e38aa3b, v30
	v_pk_add_f32 v[2:3], v[24:25], v[2:3]
	v_exp_f32_e32 v38, v0
	v_fmac_f32_e32 v30, 0x3e38aa3b, v15
	v_sub_f32_e32 v0, v236, v81
	v_pk_add_f32 v[2:3], v[34:35], v[2:3]
	v_exp_f32_e32 v30, v30
	v_mul_f32_e32 v0, 0x3e38aa3b, v0
	v_pk_add_f32 v[2:3], v[26:27], v[2:3]
	v_exp_f32_e32 v1, v1
	v_exp_f32_e32 v0, v0
	v_pk_add_f32 v[2:3], v[36:37], v[2:3]
	v_pk_fma_f32 v[16:17], v[82:83], v[242:243], v[16:17]
	v_pk_add_f32 v[2:3], v[28:29], v[2:3]
	s_add_i32 s2, s2, 64
	v_pk_add_f32 v[2:3], v[38:39], v[2:3]
	s_cmp_eq_u32 s18, s2
	v_pk_add_f32 v[2:3], v[30:31], v[2:3]
	v_lshl_add_u64 v[84:85], v[84:85], 0, s[26:27]
	v_pk_fma_f32 v[82:83], v[16:17], v[0:1], v[2:3]
	s_cbranch_scc1 .LBB0_292
	s_branch .LBB0_276

; #define KLOAD(t) do { const bf16* kp_ = Kb + (size_t)((t) * 64 + sr) * 1024 + sc; ks0 = *reinterpret_cast<const bf16x8*>(kp_); ks1 = *reinterpret_cast<const bf16x8*>(kp_ + 32 * 1024); } while (0)
; #define VLOAD(t) do { const bf16* vp_ = Vb + (size_t)((t) * 64 + sr) * 1024 + sc; vs0 = *reinterpret_cast<const bf16x8*>(vp_); vs1 = *reinterpret_cast<const bf16x8*>(vp_ + 32 * 1024); } while (0)
; #define KWRITE() do { *reinterpret_cast<bf16x8*>(K_lds + kst0) = ks0; *reinterpret_cast<bf16x8*>(K_lds + kst1) = ks1; } while (0)
; #define VWRITE() do { *reinterpret_cast<bf16x8*>(V_lds + vst0) = vs0; *reinterpret_cast<bf16x8*>(V_lds + vst1) = vs1; } while (0)
; template <bool DIFF> ...
;     ...
;   for (int t = t_lo; t < t_hi; ++t) {
;     __syncthreads();
;     KWRITE(); VWRITE();
;     __syncthreads();
;     if (t + 1 < t_hi) { KLOAD(t + 1); VLOAD(t + 1); }
;     const bool active = DIFF || (t >= rstart && t < rstart + 8);
;     if (active) {
;       bf16x8 pa0, pa1, pa2, pa3;
;     ...
;       f32x16 a0, b0, a1, b1;
;       qkt<DIFF>(a0, b0, K_lds, Q_lds, r32, r32, hi);
;       qkt<DIFF>(a1, b1, K_lds, Q_lds, r32 + 32, r32, hi);
.LBB0_310:
	s_mov_b32 s94, 0
	s_cmpk_ge_i32 s93, 0x9f
	s_cbranch_scc1 .Lsw2p_hi
	s_cmpk_le_i32 s93, 0xff41
	s_cbranch_scc0 .Lsw2p_go
	v_mov_b32_e32 v234, v252
	v_mov_b32_e32 v236, v252
	s_mov_b32 s94, 1
	s_branch .Lsw2p_go
.Lsw2p_hi:
	v_mov_b32_e32 v234, v253
	v_mov_b32_e32 v236, v253
	s_mov_b32 s94, 1
.Lsw2p_go:
	s_barrier
	s_waitcnt vmcnt(3)
	ds_write_b128 v174, v[128:131]
	s_waitcnt vmcnt(2)
	ds_write_b128 v175, v[132:135]
	s_waitcnt vmcnt(1)
	ds_write_b128 v189, v[136:139] offset:16384
	s_waitcnt vmcnt(0)
	ds_write_b128 v190, v[140:143] offset:16384
	s_waitcnt lgkmcnt(0)
	s_barrier
	s_cmp_lg_u32 s94, 0
	s_cbranch_scc1 .Lsw2f
	ds_read_b128 v[64:67], v176
	ds_read_b128 v[68:71], v172 offset:36864
	ds_read_b128 v[72:75], v177
	ds_read_b128 v[76:79], v176 offset:8192
	s_waitcnt lgkmcnt(2)
	v_mfma_f32_32x32x16_bf16 v[112:127], v[64:67], v[68:71], 0
	ds_read_b128 v[64:67], v171 offset:36864
	ds_read_b128 v[128:131], v177 offset:8192
	s_waitcnt lgkmcnt(1)
	v_mfma_f32_32x32x16_bf16 v[96:111], v[72:75], v[64:67], 0
	ds_read_b128 v[72:75], v178
	ds_read_b128 v[132:135], v170 offset:36864
	ds_read_b128 v[80:83], v179
	ds_read_b128 v[136:139], v178 offset:8192
	ds_read_b128 v[140:143], v169 offset:36864
	ds_read_b128 v[192:195], v179 offset:8192
	s_waitcnt lgkmcnt(1)
	v_mfma_f32_32x32x16_bf16 v[96:111], v[80:83], v[140:143], v[96:111]
	v_mfma_f32_32x32x16_bf16 v[112:127], v[72:75], v[132:135], v[112:127]
	ds_read_b128 v[72:75], v180
	ds_read_b128 v[196:199], v168 offset:36864
	ds_read_b128 v[80:83], v181
	ds_read_b128 v[200:203], v180 offset:8192
	ds_read_b128 v[204:207], v167 offset:36864
	ds_read_b128 v[210:213], v181 offset:8192
	s_waitcnt lgkmcnt(1)
	v_mfma_f32_32x32x16_bf16 v[96:111], v[80:83], v[204:207], v[96:111]
	v_mfma_f32_32x32x16_bf16 v[112:127], v[72:75], v[196:199], v[112:127]
	ds_read_b128 v[72:75], v182
	ds_read_b128 v[214:217], v166 offset:36864
	ds_read_b128 v[80:83], v183
	ds_read_b128 v[218:221], v182 offset:8192
	ds_read_b128 v[222:225], v149 offset:36864
	ds_read_b128 v[226:229], v183 offset:8192
	s_waitcnt lgkmcnt(1)
	v_mfma_f32_32x32x16_bf16 v[96:111], v[80:83], v[222:225], v[96:111]
	v_mfma_f32_32x32x16_bf16 v[80:95], v[76:79], v[68:71], 0
	v_mfma_f32_32x32x16_bf16 v[112:127], v[72:75], v[214:217], v[112:127]
	v_mfma_f32_32x32x16_bf16 v[64:79], v[128:131], v[64:67], 0
	v_lshl_add_u64 v[128:129], v[150:151], 0, s[34:35]
	v_add_co_u32_e32 v130, vcc, s70, v128
	s_nop 1
	v_addc_co_u32_e32 v131, vcc, 0, v129, vcc
	v_mfma_f32_32x32x16_bf16 v[80:95], v[136:139], v[132:135], v[80:95]
	v_add_co_u32_e32 v132, vcc, s71, v128
	v_lshl_add_u64 v[136:137], v[152:153], 0, s[34:35]
	s_nop 0
	v_addc_co_u32_e32 v133, vcc, 0, v129, vcc
	v_add_co_u32_e32 v138, vcc, s72, v136
	v_mfma_f32_32x32x16_bf16 v[64:79], v[192:195], v[140:143], v[64:79]
	s_nop 0
	v_addc_co_u32_e32 v139, vcc, 0, v137, vcc
	v_add_co_u32_e32 v140, vcc, s73, v136
	global_load_dwordx4 v[128:131], v[130:131], off
	s_nop 0
	global_load_dwordx4 v[132:135], v[132:133], off
	v_addc_co_u32_e32 v141, vcc, 0, v137, vcc
	global_load_dwordx4 v[136:139], v[138:139], off
	s_nop 0
	global_load_dwordx4 v[140:143], v[140:141], off
	v_mfma_f32_32x32x16_bf16 v[80:95], v[200:203], v[196:199], v[80:95]
	v_mfma_f32_32x32x16_bf16 v[64:79], v[210:213], v[204:207], v[64:79]
	v_mfma_f32_32x32x16_bf16 v[80:95], v[218:221], v[214:217], v[80:95]
	s_waitcnt lgkmcnt(0)
	v_mfma_f32_32x32x16_bf16 v[64:79], v[226:229], v[222:225], v[64:79]
	s_cmpk_ge_i32 s93, 0x9f
	s_cbranch_scc1 .Lb2a_hi
	s_cmpk_le_i32 s93, 0xff41
	s_cbranch_scc1 .Lb2a_lo
	v_add3_u32 v192, v191, v173, s55
	v_med3_i32 v193, v192, 0, v163
	v_lshl_add_u32 v200, v193, 2, 0
	v_max_i32_e32 v193, -1, v192
	v_add_u32_e32 v193, 1, v193
	v_min_u32_e32 v193, 0x100, v193
	v_lshl_add_u32 v201, v193, 2, 0
	v_max_i32_e32 v193, -2, v192
	v_add_u32_e32 v193, 2, v193
	v_min_u32_e32 v193, 0x100, v193
	v_lshl_add_u32 v202, v193, 2, 0
	v_max_i32_e32 v193, -3, v192
	v_add_u32_e32 v193, 3, v193
	v_min_u32_e32 v193, 0x100, v193
	v_lshl_add_u32 v203, v193, 2, 0
	v_max_i32_e32 v193, -8, v192
	v_add_u32_e32 v193, 8, v193
	v_min_u32_e32 v193, 0x100, v193
	v_lshl_add_u32 v204, v193, 2, 0
	v_max_i32_e32 v193, -9, v192
	v_add_u32_e32 v193, 9, v193
	v_min_u32_e32 v193, 0x100, v193
	v_lshl_add_u32 v205, v193, 2, 0
	v_max_i32_e32 v193, -10, v192
	v_add_u32_e32 v193, 10, v193
	v_min_u32_e32 v193, 0x100, v193
	v_lshl_add_u32 v206, v193, 2, 0
	v_max_i32_e32 v193, -11, v192
	v_add_u32_e32 v193, 11, v193
	v_min_u32_e32 v193, 0x100, v193
	v_lshl_add_u32 v207, v193, 2, 0
	v_max_i32_e32 v193, -16, v192
	v_max_i32_e32 v194, 0xffffffef, v192
	v_max_i32_e32 v195, 0xffffffee, v192
	v_max_i32_e32 v196, 0xffffffed, v192
	v_max_i32_e32 v197, 0xffffffe8, v192
	v_max_i32_e32 v198, 0xffffffe7, v192
	v_max_i32_e32 v199, 0xffffffe6, v192
	v_add_u32_e32 v193, 16, v193
	v_add_u32_e32 v194, 17, v194
	v_add_u32_e32 v195, 18, v195
	v_add_u32_e32 v196, 19, v196
	v_add_u32_e32 v197, 24, v197
	v_add_u32_e32 v198, 25, v198
	v_add_u32_e32 v199, 26, v199
	v_max_i32_e32 v192, 0xffffffe5, v192
	v_min_u32_e32 v193, 0x100, v193
	v_min_u32_e32 v194, 0x100, v194
	v_min_u32_e32 v195, 0x100, v195
	v_min_u32_e32 v196, 0x100, v196
	v_min_u32_e32 v197, 0x100, v197
	v_min_u32_e32 v198, 0x100, v198
	v_min_u32_e32 v199, 0x100, v199
	v_add_u32_e32 v192, 27, v192
	v_lshl_add_u32 v193, v193, 2, 0
	v_lshl_add_u32 v194, v194, 2, 0
	v_lshl_add_u32 v195, v195, 2, 0
	v_lshl_add_u32 v196, v196, 2, 0
	v_lshl_add_u32 v197, v197, 2, 0
	v_lshl_add_u32 v198, v198, 2, 0
	v_lshl_add_u32 v199, v199, 2, 0
	v_min_u32_e32 v192, 0x100, v192
	v_lshl_add_u32 v209, v192, 2, 0
	ds_read_b32 v192, v193 offset:32768
	ds_read_b32 v193, v194 offset:32768
	ds_read_b32 v194, v195 offset:32768
	ds_read_b32 v195, v196 offset:32768
	ds_read_b32 v196, v197 offset:32768
	ds_read_b32 v197, v198 offset:32768
	ds_read_b32 v198, v199 offset:32768
	ds_read_b32 v199, v209 offset:32768
	ds_read_b32 v200, v200 offset:32768
	ds_read_b32 v201, v201 offset:32768
	ds_read_b32 v202, v202 offset:32768
	ds_read_b32 v203, v203 offset:32768
	ds_read_b32 v204, v204 offset:32768
	ds_read_b32 v205, v205 offset:32768
	ds_read_b32 v206, v206 offset:32768
	ds_read_b32 v207, v207 offset:32768
	s_waitcnt lgkmcnt(8)
	v_pk_add_f32 v[126:127], v[126:127], v[198:199]
	v_pk_add_f32 v[124:125], v[124:125], v[196:197]
	v_pk_add_f32 v[122:123], v[122:123], v[194:195]
	v_pk_add_f32 v[120:121], v[120:121], v[192:193]
	s_waitcnt lgkmcnt(0)
	v_pk_add_f32 v[118:119], v[118:119], v[206:207]
	v_pk_add_f32 v[116:117], v[116:117], v[204:205]
	v_pk_add_f32 v[114:115], v[114:115], v[202:203]
	v_pk_add_f32 v[112:113], v[112:113], v[200:201]
	v_pk_add_f32 v[110:111], v[110:111], v[198:199]
	v_pk_add_f32 v[108:109], v[108:109], v[196:197]
	v_pk_add_f32 v[106:107], v[106:107], v[194:195]
	v_pk_add_f32 v[104:105], v[104:105], v[192:193]
	v_pk_add_f32 v[102:103], v[102:103], v[206:207]
	v_pk_add_f32 v[100:101], v[100:101], v[204:205]
	v_pk_add_f32 v[98:99], v[98:99], v[202:203]
	v_pk_add_f32 v[96:97], v[96:97], v[200:201]
	v_mov_b32_e32 v192, 0
	s_branch .LBB0_318

; #define SBAR() __builtin_amdgcn_sched_barrier(0)
; template <bool DIFF>
; __device__ __forceinline__ void qkt(f32x16& a, f32x16& b, const char* Ks, const char* Qs, int krow, int r32, int hi) {
;   a = f32x16{}; b = f32x16{};
; #pragma unroll
;   for (int d = 0; d < 4; ++d) {
;     const int cb0 = (d * 16 + hi * 8) * 2, cb1 = ((d + 4) * 16 + hi * 8) * 2;
;     const bf16x8 k0 = *reinterpret_cast<const bf16x8*>(Ks + KSWZ(krow, cb0)), q0 = *reinterpret_cast<const bf16x8*>(Qs + KSWZ(r32, cb0));
;     const bf16x8 k1 = *reinterpret_cast<const bf16x8*>(Ks + KSWZ(krow, cb1)), q1 = *reinterpret_cast<const bf16x8*>(Qs + KSWZ(r32, cb1));
;     a = __builtin_amdgcn_mfma_f32_32x32x16_bf16(k0, q0, a, 0, 0, 0);
;     b = __builtin_amdgcn_mfma_f32_32x32x16_bf16(k1, q1, b, 0, 0, 0); }
; template <bool DIFF> ...
;     ...
;       BIAS_APPLY(t, 0, a0, b0, cb0);
;       { const float x1 = fmaf(cb0, C, e1), x2 = fmaf(cb0, C, e2);
; #pragma unroll
;       for (int r = 0; r < 16; ++r) a0[r] = __builtin_amdgcn_exp2f(fmaf(a0[r], C, x1));
;       if (DIFF) {
; #pragma unroll
;         for (int r = 0; r < 16; ++r) a0[r] = fmaf(nsg, __builtin_amdgcn_exp2f(fmaf(b0[r], C, x2)), a0[r]);
;       } }
;       PK4(a0, 0, pa0); PK4(a0, 8, pa1);
;       SBAR();
;       pv_step<0>(o, vb0, pa0); pv_step<1>(o, vb0, pa1);
.Lb2b_lo:
	v_mov_b32_e32 v96, v252
	s_branch .LBB0_309
.Lsw2f:
	ds_read_b128 v[64:67], v176
	ds_read_b128 v[68:71], v172 offset:36864
	ds_read_b128 v[72:75], v177
	ds_read_b128 v[76:79], v176 offset:8192
	s_waitcnt lgkmcnt(2)
	v_mfma_f32_32x32x16_bf16 v[112:127], v[64:67], v[68:71], 0
	ds_read_b128 v[64:67], v171 offset:36864
	ds_read_b128 v[128:131], v177 offset:8192
	s_waitcnt lgkmcnt(1)
	v_mfma_f32_32x32x16_bf16 v[96:111], v[72:75], v[64:67], 0
	ds_read_b128 v[72:75], v178
	ds_read_b128 v[132:135], v170 offset:36864
	ds_read_b128 v[80:83], v179
	ds_read_b128 v[136:139], v178 offset:8192
	ds_read_b128 v[140:143], v169 offset:36864
	ds_read_b128 v[192:195], v179 offset:8192
	s_waitcnt lgkmcnt(1)
	v_mfma_f32_32x32x16_bf16 v[96:111], v[80:83], v[140:143], v[96:111]
	v_mfma_f32_32x32x16_bf16 v[112:127], v[72:75], v[132:135], v[112:127]
	ds_read_b128 v[72:75], v180
	ds_read_b128 v[196:199], v168 offset:36864
	ds_read_b128 v[80:83], v181
	ds_read_b128 v[200:203], v180 offset:8192
	ds_read_b128 v[204:207], v167 offset:36864
	ds_read_b128 v[210:213], v181 offset:8192
	s_waitcnt lgkmcnt(1)
	v_mfma_f32_32x32x16_bf16 v[96:111], v[80:83], v[204:207], v[96:111]
	v_mfma_f32_32x32x16_bf16 v[112:127], v[72:75], v[196:199], v[112:127]
	ds_read_b128 v[72:75], v182
	ds_read_b128 v[214:217], v166 offset:36864
	ds_read_b128 v[80:83], v183
	ds_read_b128 v[218:221], v182 offset:8192
	ds_read_b128 v[222:225], v149 offset:36864
	ds_read_b128 v[226:229], v183 offset:8192
	s_waitcnt lgkmcnt(1)
	v_mfma_f32_32x32x16_bf16 v[96:111], v[80:83], v[222:225], v[96:111]
	v_mfma_f32_32x32x16_bf16 v[112:127], v[72:75], v[214:217], v[112:127]
	s_waitcnt lgkmcnt(0)
	v_mfma_f32_32x32x16_bf16 v[80:95], v[76:79], v[68:71], 0
	v_fmamk_f32 v235, v234, 0x3e38aa3b, v188
	v_fmamk_f32 v234, v234, 0x3e38aa3b, v187
	s_nop 8
	v_fmamk_f32 v112, v112, 0x3e38aa3b, v235
	v_fmamk_f32 v113, v113, 0x3e38aa3b, v235
	v_fmamk_f32 v114, v114, 0x3e38aa3b, v235
	v_fmamk_f32 v115, v115, 0x3e38aa3b, v235
	v_fmamk_f32 v116, v116, 0x3e38aa3b, v235
	v_fmamk_f32 v117, v117, 0x3e38aa3b, v235
	v_fmamk_f32 v96, v96, 0x3e38aa3b, v234
	v_fmamk_f32 v97, v97, 0x3e38aa3b, v234
	v_fmamk_f32 v98, v98, 0x3e38aa3b, v234
	v_fmamk_f32 v99, v99, 0x3e38aa3b, v234
	v_fmamk_f32 v100, v100, 0x3e38aa3b, v234
	v_fmamk_f32 v101, v101, 0x3e38aa3b, v234
	v_exp_f32_e32 v112, v112
	v_mfma_f32_32x32x16_bf16 v[64:79], v[128:131], v[64:67], 0
	v_exp_f32_e32 v113, v113
	v_exp_f32_e32 v114, v114
	v_exp_f32_e32 v115, v115
	v_exp_f32_e32 v116, v116
	v_exp_f32_e32 v117, v117
	v_fmamk_f32 v118, v118, 0x3e38aa3b, v235
	v_fmamk_f32 v119, v119, 0x3e38aa3b, v235
	v_fmamk_f32 v120, v120, 0x3e38aa3b, v235
	v_fmamk_f32 v121, v121, 0x3e38aa3b, v235
	v_fmamk_f32 v122, v122, 0x3e38aa3b, v235
	v_mfma_f32_32x32x16_bf16 v[80:95], v[136:139], v[132:135], v[80:95]
	v_fmamk_f32 v123, v123, 0x3e38aa3b, v235
	v_fmamk_f32 v124, v124, 0x3e38aa3b, v235
	v_fmamk_f32 v125, v125, 0x3e38aa3b, v235
	v_fmamk_f32 v126, v126, 0x3e38aa3b, v235
	v_fmac_f32_e32 v235, 0x3e38aa3b, v127
	v_exp_f32_e32 v96, v96
	v_exp_f32_e32 v97, v97
	v_exp_f32_e32 v98, v98
	v_exp_f32_e32 v99, v99
	v_exp_f32_e32 v100, v100
	v_exp_f32_e32 v101, v101
	v_mfma_f32_32x32x16_bf16 v[64:79], v[192:195], v[140:143], v[64:79]
	v_lshl_add_u64 v[128:129], v[150:151], 0, s[34:35]
	v_add_co_u32_e32 v130, vcc, s70, v128
	s_nop 1
	v_addc_co_u32_e32 v131, vcc, 0, v129, vcc
	v_add_co_u32_e32 v132, vcc, s71, v128
	v_lshl_add_u64 v[136:137], v[152:153], 0, s[34:35]
	s_nop 0
	v_addc_co_u32_e32 v133, vcc, 0, v129, vcc
	v_add_co_u32_e32 v138, vcc, s72, v136
	s_nop 1
	v_addc_co_u32_e32 v139, vcc, 0, v137, vcc
	v_add_co_u32_e32 v140, vcc, s73, v136
	global_load_dwordx4 v[128:131], v[130:131], off
	s_nop 0
	global_load_dwordx4 v[132:135], v[132:133], off
	v_addc_co_u32_e32 v141, vcc, 0, v137, vcc
	global_load_dwordx4 v[136:139], v[138:139], off
	s_nop 0
	global_load_dwordx4 v[140:143], v[140:141], off
	v_fmamk_f32 v102, v102, 0x3e38aa3b, v234
	v_fmamk_f32 v103, v103, 0x3e38aa3b, v234
	v_fmamk_f32 v104, v104, 0x3e38aa3b, v234
	v_fmamk_f32 v105, v105, 0x3e38aa3b, v234
	v_fmamk_f32 v106, v106, 0x3e38aa3b, v234
	v_fmamk_f32 v107, v107, 0x3e38aa3b, v234
	v_fmamk_f32 v108, v108, 0x3e38aa3b, v234
	v_fmamk_f32 v109, v109, 0x3e38aa3b, v234
	v_fmamk_f32 v110, v110, 0x3e38aa3b, v234
	v_fmac_f32_e32 v234, 0x3e38aa3b, v111
	v_exp_f32_e32 v118, v118
	v_exp_f32_e32 v119, v119
	v_exp_f32_e32 v120, v120
	v_mfma_f32_32x32x16_bf16 v[80:95], v[200:203], v[196:199], v[80:95]
	v_exp_f32_e32 v121, v121
	v_exp_f32_e32 v122, v122
	v_exp_f32_e32 v123, v123
	v_exp_f32_e32 v124, v124
	v_exp_f32_e32 v125, v125
	v_exp_f32_e32 v126, v126
	v_exp_f32_e32 v127, v235
	v_exp_f32_e32 v102, v102
	v_mfma_f32_32x32x16_bf16 v[64:79], v[210:213], v[204:207], v[64:79]
	v_exp_f32_e32 v103, v103
	v_exp_f32_e32 v104, v104
	v_exp_f32_e32 v105, v105
	v_exp_f32_e32 v106, v106
	v_exp_f32_e32 v107, v107
	v_exp_f32_e32 v108, v108
	v_exp_f32_e32 v109, v109
	v_exp_f32_e32 v110, v110
	v_mfma_f32_32x32x16_bf16 v[80:95], v[218:221], v[214:217], v[80:95]
	v_exp_f32_e32 v111, v234
	v_pk_fma_f32 v[96:97], v[144:145], v[96:97], v[112:113]
	v_pk_fma_f32 v[98:99], v[144:145], v[98:99], v[114:115]
	v_pk_fma_f32 v[100:101], v[144:145], v[100:101], v[116:117]
	v_pk_fma_f32 v[102:103], v[144:145], v[102:103], v[118:119]
	v_pk_fma_f32 v[104:105], v[144:145], v[104:105], v[120:121]
	v_pk_fma_f32 v[106:107], v[144:145], v[106:107], v[122:123]
	v_pk_fma_f32 v[108:109], v[144:145], v[108:109], v[124:125]
	v_mfma_f32_32x32x16_bf16 v[64:79], v[226:229], v[222:225], v[64:79]
	v_pk_fma_f32 v[110:111], v[144:145], v[110:111], v[126:127]
	v_cvt_pk_bf16_f32 v96, v96, v97
	v_cvt_pk_bf16_f32 v97, v98, v99
; #define SBAR() __builtin_amdgcn_sched_barrier(0)
; template <bool DIFF> ...
;     ...
;       PK4(a0, 0, pa0); PK4(a0, 8, pa1);
;       SBAR();
;       pv_step<0>(o, vb0, pa0); pv_step<1>(o, vb0, pa1);
;       SBAR();
;       BIAS_APPLY(t, 1, a1, b1, cb1);
;       { const float x1 = fmaf(cb1, C, e1), x2 = fmaf(cb1, C, e2);
; #pragma unroll
;       for (int r = 0; r < 16; ++r) a1[r] = __builtin_amdgcn_exp2f(fmaf(a1[r], C, x1));
;       if (DIFF) {
; #pragma unroll
;         for (int r = 0; r < 16; ++r) a1[r] = fmaf(nsg, __builtin_amdgcn_exp2f(fmaf(b1[r], C, x2)), a1[r]);
;       } }
;       PK4(a1, 0, pa2); PK4(a1, 8, pa3);
;       SBAR();
;       pv_step<2>(o, vb0, pa2); pv_step<3>(o, vb0, pa3);
	v_cvt_pk_bf16_f32 v98, v100, v101
	v_cvt_pk_bf16_f32 v99, v102, v103
	s_nop 0
	v_permlane32_swap_b32_e32 v96, v98
	v_cvt_pk_bf16_f32 v100, v104, v105
	v_cvt_pk_bf16_f32 v101, v106, v107
	v_cvt_pk_bf16_f32 v102, v108, v109
	v_cvt_pk_bf16_f32 v103, v110, v111
	v_permlane32_swap_b32_e32 v97, v99
	v_permlane32_swap_b32_e32 v100, v102
	v_permlane32_swap_b32_e32 v101, v103
	ds_read_b64_tr_b16 v[104:105], v146 offset:0
	ds_read_b64_tr_b16 v[106:107], v146 offset:0x800
	ds_read_b64_tr_b16 v[108:109], v146 offset:0x200
	ds_read_b64_tr_b16 v[110:111], v146 offset:0xa00
	ds_read_b64_tr_b16 v[112:113], v146 offset:0x400
	ds_read_b64_tr_b16 v[114:115], v146 offset:0xc00
	ds_read_b64_tr_b16 v[116:117], v146 offset:0x600
	ds_read_b64_tr_b16 v[118:119], v146 offset:0xe00
	ds_read_b64_tr_b16 v[238:239], v146 offset:0x1000
	ds_read_b64_tr_b16 v[240:241], v146 offset:0x1800
	ds_read_b64_tr_b16 v[242:243], v146 offset:0x1200
	ds_read_b64_tr_b16 v[244:245], v146 offset:0x1a00
	ds_read_b64_tr_b16 v[246:247], v146 offset:0x1400
	ds_read_b64_tr_b16 v[248:249], v146 offset:0x1c00
	ds_read_b64_tr_b16 v[120:121], v146 offset:0x1600
	ds_read_b64_tr_b16 v[122:123], v146 offset:0x1e00
	v_fmamk_f32 v237, v236, 0x3e38aa3b, v188
	v_fmamk_f32 v236, v236, 0x3e38aa3b, v187
	v_fmamk_f32 v80, v80, 0x3e38aa3b, v237
	v_fmamk_f32 v81, v81, 0x3e38aa3b, v237
	v_fmamk_f32 v82, v82, 0x3e38aa3b, v237
	v_fmamk_f32 v83, v83, 0x3e38aa3b, v237
	v_fmamk_f32 v84, v84, 0x3e38aa3b, v237
	v_fmamk_f32 v85, v85, 0x3e38aa3b, v237
	v_fmamk_f32 v86, v86, 0x3e38aa3b, v237
	v_fmamk_f32 v87, v87, 0x3e38aa3b, v237
	s_waitcnt lgkmcnt(0)
	v_mfma_f32_32x32x16_bf16 v[0:15], v[96:99], v[104:107], v[0:15]
	v_fmamk_f32 v88, v88, 0x3e38aa3b, v237
	v_fmamk_f32 v89, v89, 0x3e38aa3b, v237
	v_fmamk_f32 v90, v90, 0x3e38aa3b, v237
	v_fmamk_f32 v91, v91, 0x3e38aa3b, v237
	v_fmamk_f32 v92, v92, 0x3e38aa3b, v237
	v_fmamk_f32 v93, v93, 0x3e38aa3b, v237
	v_fmamk_f32 v94, v94, 0x3e38aa3b, v237
	v_fmac_f32_e32 v237, 0x3e38aa3b, v95
	v_fmamk_f32 v64, v64, 0x3e38aa3b, v236
	v_fmamk_f32 v65, v65, 0x3e38aa3b, v236
	v_fmamk_f32 v66, v66, 0x3e38aa3b, v236
	v_fmamk_f32 v67, v67, 0x3e38aa3b, v236
	v_fmamk_f32 v68, v68, 0x3e38aa3b, v236
	v_fmamk_f32 v69, v69, 0x3e38aa3b, v236
	v_fmamk_f32 v70, v70, 0x3e38aa3b, v236
	v_mfma_f32_32x32x16_bf16 v[16:31], v[96:99], v[108:111], v[16:31]
	v_fmamk_f32 v71, v71, 0x3e38aa3b, v236
	v_fmamk_f32 v72, v72, 0x3e38aa3b, v236
	v_fmamk_f32 v73, v73, 0x3e38aa3b, v236
	v_fmamk_f32 v74, v74, 0x3e38aa3b, v236
	v_fmamk_f32 v75, v75, 0x3e38aa3b, v236
	v_fmamk_f32 v76, v76, 0x3e38aa3b, v236
	v_fmamk_f32 v77, v77, 0x3e38aa3b, v236
	v_fmamk_f32 v78, v78, 0x3e38aa3b, v236
	v_fmac_f32_e32 v236, 0x3e38aa3b, v79
	v_exp_f32_e32 v80, v80
	v_exp_f32_e32 v81, v81
	v_exp_f32_e32 v82, v82
	v_mfma_f32_32x32x16_bf16 v[32:47], v[96:99], v[112:115], v[32:47]
	v_exp_f32_e32 v83, v83
	v_exp_f32_e32 v84, v84
	v_exp_f32_e32 v85, v85
	v_exp_f32_e32 v86, v86
	v_exp_f32_e32 v87, v87
	v_exp_f32_e32 v88, v88
	v_exp_f32_e32 v89, v89
	v_mfma_f32_32x32x16_bf16 v[48:63], v[96:99], v[116:119], v[48:63]
	v_exp_f32_e32 v90, v90
	v_exp_f32_e32 v91, v91
	v_exp_f32_e32 v92, v92
	v_exp_f32_e32 v93, v93
	v_exp_f32_e32 v94, v94
	v_exp_f32_e32 v95, v237
	v_exp_f32_e32 v64, v64
	v_mfma_f32_32x32x16_bf16 v[0:15], v[100:103], v[238:241], v[0:15]
	v_exp_f32_e32 v65, v65
	v_exp_f32_e32 v66, v66
	v_exp_f32_e32 v67, v67
	v_exp_f32_e32 v68, v68
	v_exp_f32_e32 v69, v69
	v_exp_f32_e32 v70, v70
	v_exp_f32_e32 v71, v71
	v_mfma_f32_32x32x16_bf16 v[16:31], v[100:103], v[242:245], v[16:31]
	v_exp_f32_e32 v72, v72
	v_exp_f32_e32 v73, v73
	v_exp_f32_e32 v74, v74
	v_exp_f32_e32 v75, v75
	v_exp_f32_e32 v76, v76
	v_exp_f32_e32 v77, v77
	v_exp_f32_e32 v78, v78
	v_mfma_f32_32x32x16_bf16 v[32:47], v[100:103], v[246:249], v[32:47]
	v_exp_f32_e32 v79, v236
	v_pk_fma_f32 v[64:65], v[144:145], v[64:65], v[80:81]
	v_pk_fma_f32 v[66:67], v[144:145], v[66:67], v[82:83]
	v_pk_fma_f32 v[68:69], v[144:145], v[68:69], v[84:85]
	v_pk_fma_f32 v[70:71], v[144:145], v[70:71], v[86:87]
	v_pk_fma_f32 v[72:73], v[144:145], v[72:73], v[88:89]
	v_pk_fma_f32 v[74:75], v[144:145], v[74:75], v[90:91]
	v_mfma_f32_32x32x16_bf16 v[48:63], v[100:103], v[120:123], v[48:63]
	v_pk_fma_f32 v[76:77], v[144:145], v[76:77], v[92:93]
	v_pk_fma_f32 v[78:79], v[144:145], v[78:79], v[94:95]
	v_cvt_pk_bf16_f32 v64, v64, v65
	v_cvt_pk_bf16_f32 v65, v66, v67
	v_cvt_pk_bf16_f32 v66, v68, v69
	v_cvt_pk_bf16_f32 v67, v70, v71
	v_cvt_pk_bf16_f32 v68, v72, v73
	v_cvt_pk_bf16_f32 v69, v74, v75
	v_cvt_pk_bf16_f32 v70, v76, v77
	v_cvt_pk_bf16_f32 v71, v78, v79
	v_permlane32_swap_b32_e32 v64, v66
	v_permlane32_swap_b32_e32 v65, v67
	v_permlane32_swap_b32_e32 v68, v70
	v_permlane32_swap_b32_e32 v69, v71
	ds_read_b64_tr_b16 v[72:73], v146 offset:0x2000
	ds_read_b64_tr_b16 v[74:75], v146 offset:0x2800
	ds_read_b64_tr_b16 v[76:77], v146 offset:0x2200
	ds_read_b64_tr_b16 v[78:79], v146 offset:0x2a00
	ds_read_b64_tr_b16 v[80:81], v146 offset:0x2400
	ds_read_b64_tr_b16 v[82:83], v146 offset:0x2c00
	ds_read_b64_tr_b16 v[84:85], v146 offset:0x2600
	ds_read_b64_tr_b16 v[86:87], v146 offset:0x2e00
	ds_read_b64_tr_b16 v[238:239], v146 offset:0x3000
	ds_read_b64_tr_b16 v[240:241], v146 offset:0x3800
	ds_read_b64_tr_b16 v[242:243], v146 offset:0x3200
	ds_read_b64_tr_b16 v[244:245], v146 offset:0x3a00
	ds_read_b64_tr_b16 v[246:247], v146 offset:0x3400
	ds_read_b64_tr_b16 v[248:249], v146 offset:0x3c00
	ds_read_b64_tr_b16 v[88:89], v146 offset:0x3600
	ds_read_b64_tr_b16 v[90:91], v146 offset:0x3e00
	s_waitcnt lgkmcnt(8)
	v_mfma_f32_32x32x16_bf16 v[0:15], v[64:67], v[72:75], v[0:15]
	v_mfma_f32_32x32x16_bf16 v[16:31], v[64:67], v[76:79], v[16:31]
	v_mfma_f32_32x32x16_bf16 v[32:47], v[64:67], v[80:83], v[32:47]
	v_mfma_f32_32x32x16_bf16 v[48:63], v[64:67], v[84:87], v[48:63]
	s_waitcnt lgkmcnt(0)
	v_mfma_f32_32x32x16_bf16 v[0:15], v[68:71], v[238:241], v[0:15]
	s_add_u32 s34, s34, 0x20000
	s_addc_u32 s35, s35, 0
	v_add_u32_e32 v173, 64, v173
	s_add_i32 s93, s93, 64
	s_cmp_eq_u32 s2, s34
	v_mfma_f32_32x32x16_bf16 v[16:31], v[68:71], v[242:245], v[16:31]
	v_mfma_f32_32x32x16_bf16 v[32:47], v[68:71], v[246:249], v[32:47]
	v_mfma_f32_32x32x16_bf16 v[48:63], v[68:71], v[88:91], v[48:63]
	s_cbranch_scc1 .LBB0_326
	s_branch .LBB0_310
